# flat grid barriers: the polling wave's four arrival-flag loads per lane issued together and waited once (they were four dependent round trips from a short-circuit &&)
# speedup vs baseline: 1.0180x; 1.0107x over previous
.LBB0_122:
	global_load_dword v2, v[4:5], off sc1
	global_load_dword v6, v[4:5], off offset:256 sc1
	global_load_dword v7, v[4:5], off offset:512 sc1
	global_load_dword v8, v[4:5], off offset:768 sc1
	s_mov_b64 s[22:23], -1
	s_waitcnt vmcnt(0)
	v_min_u32_e32 v2, v2, v6
	v_min3_u32 v2, v2, v7, v8
	v_cmp_eq_u32_e64 s[38:39], 0, v2
	v_cndmask_b32_e64 v2, 0, 1, s[38:39]
	v_cmp_ne_u32_e32 vcc, 0, v2
	s_mov_b64 s[24:25], -1
	s_cbranch_vccz .LBB0_121
	s_and_b32 s1, s0, 0xff
	s_cmp_eq_u32 s1, 0
	s_mov_b64 s[38:39], -1
	s_sleep 1
	s_cbranch_scc0 .LBB0_132
	global_load_dword v2, v3, s[34:35] sc1
	s_waitcnt vmcnt(0)
	v_cmp_eq_u32_e32 vcc, 0, v2
	s_cbranch_vccnz .LBB0_134
	s_mov_b64 s[38:39], 0

.LBB0_514:
	global_load_dword v2, v[4:5], off sc1
	global_load_dword v6, v[4:5], off offset:256 sc1
	global_load_dword v7, v[4:5], off offset:512 sc1
	global_load_dword v8, v[4:5], off offset:768 sc1
	s_mov_b64 s[8:9], -1
	s_waitcnt vmcnt(0)
	v_min_u32_e32 v2, v2, v6
	v_min3_u32 v2, v2, v7, v8
	v_cmp_gt_u32_e64 s[12:13], 2, v2
	v_cndmask_b32_e64 v2, 0, 1, s[12:13]
	v_cmp_ne_u32_e32 vcc, 0, v2
	s_mov_b64 s[10:11], -1
	s_cbranch_vccz .LBB0_513
	s_and_b32 s1, s0, 0xff
	s_cmp_eq_u32 s1, 0
	s_mov_b64 s[12:13], -1
	s_sleep 1
	s_cbranch_scc0 .LBB0_524
	global_load_dword v2, v3, s[34:35] sc1
	s_waitcnt vmcnt(0)
	v_cmp_eq_u32_e32 vcc, 0, v2
	s_cbranch_vccnz .LBB0_526
	s_mov_b64 s[12:13], 0
